# combined DSA attention trims: full-nsel fast path + exact 0.125 scale fold + sparse counted waits
# speedup vs baseline: 1.0057x; 1.0057x over previous
;   __device__ __forceinline__ half_t* mm() const { return (half_t*)(ws() + OFF_mm); }
; __device__ __forceinline__ void dsa_item(const KP& p, int b, int tile, char* smem) {
;     ...
;     const int nsel = min(cnt[tk], 256);
;     const half_t* urow = ub + (size_t)t * NU;
;     const int col = lane & 15;
;     h8 q0, q1;
; #pragma unroll
;     for (int e = 0; e < 8; ++e) { q0[e] = (half_t)0.f; q1[e] = (half_t)0.f; }
;     if (col < 8) {
;       q0 = *(const h8*)(urow + C_BQ + col * 64 + hq * 8);
;       q1 = *(const h8*)(urow + C_BQ + col * 64 + 32 + hq * 8);
;     }
;     float mx = NEGF;
; #pragma unroll 1
;     for (int mg = 0; mg < 2; ++mg) {
; #pragma unroll
;       for (int mm = 0; mm < 8; ++mm) {
;         const int m = mg * 8 + mm;
;         const int pos = m * 16 + col;
;         const int s = (pos < nsel) ? (int)sel[tk * 256 + pos] : 0;
;         const half_t* kp = ub + (size_t)s * NU + C_BK + hq * 8;
;         const h8 a0 = *(const h8*)kp, a1 = *(const h8*)(kp + 32);
;         f32x4 d = {0.f, 0.f, 0.f, 0.f};
.LBB0_1427:
	s_or_b64 exec, exec, s[2:3]
	s_waitcnt lgkmcnt(0)
	v_min_i32_e32 v85, 0x100, v11
	v_lshlrev_b32_e32 v14, 9, v10
	v_mov_b32_e32 v15, 0xf149f2ca
	s_add_u32 s14, s78, 0x3800
	s_addc_u32 s15, s79, 0
	v_add_u32_e32 v203, v126, v157
	v_lshl_add_u32 v80, v203, 1, v14
	ds_read_u16 v172, v80 offset:32768
	ds_read_u16 v173, v80 offset:32896
	ds_read_u16 v174, v80 offset:33024
	ds_read_u16 v175, v80 offset:33152
	v_and_b32_e32 v200, 7, v157
	v_lshlrev_b32_e32 v200, 4, v200
	v_mul_u32_u24_e32 v201, 0x240, v159
	v_add_u32_e32 v201, 0xa800, v201
	v_mul_u32_u24_e32 v198, 0x90, v165
	v_add3_u32 v198, v198, v200, v201
	v_mul_u32_u24_e32 v199, 0x90, v157
	v_add3_u32 v199, v199, v126, v201
	v_lshlrev_b32_e32 v202, 8, v159
	v_add_u32_e32 v202, 0xcc00, v202
	v_lshl_add_u32 v81, v203, 2, v202
	v_add_u32_e32 v171, -1, v85
	v_add_u32_e32 v156, -2, v85
	v_add_u32_e32 v158, -3, v85
	v_cmp_lt_i32_e32 vcc, v203, v85
	s_waitcnt lgkmcnt(3)
	s_nop 0
	v_cndmask_b32_e32 v172, 0, v172, vcc
	v_mul_u32_u24_e32 v172, 0x3a00, v172
	ds_write_b32 v81, v172
	v_add_u32_e32 v201, 64, v203
	v_cmp_lt_i32_e32 vcc, v201, v85
	s_waitcnt lgkmcnt(2)
	s_nop 0
	v_cndmask_b32_e32 v173, 0, v173, vcc
	v_mul_u32_u24_e32 v173, 0x3a00, v173
	ds_write_b32 v81, v173 offset:256
	v_add_u32_e32 v201, 0x80, v203
	v_cmp_lt_i32_e32 vcc, v201, v85
	s_waitcnt lgkmcnt(1)
	s_nop 0
	v_cndmask_b32_e32 v174, 0, v174, vcc
	v_mul_u32_u24_e32 v174, 0x3a00, v174
	ds_write_b32 v81, v174 offset:512
	v_add_u32_e32 v201, 0xc0, v203
	v_cmp_lt_i32_e32 vcc, v201, v85
	s_waitcnt lgkmcnt(0)
	s_nop 0
	v_cndmask_b32_e32 v175, 0, v175, vcc
	v_mul_u32_u24_e32 v175, 0x3a00, v175
	ds_write_b32 v81, v175 offset:768
	v_lshl_add_u32 v202, v165, 2, v202
	ds_read_b32 v172, v202
	ds_read_b32 v173, v202 offset:64
	ds_read_b32 v174, v202 offset:128
	ds_read_b32 v175, v202 offset:192
	ds_read_b32 v176, v202 offset:256
	ds_read_b32 v177, v202 offset:320
	ds_read_b32 v178, v202 offset:384
	ds_read_b32 v179, v202 offset:448
	ds_read_b32 v180, v202 offset:512
	ds_read_b32 v181, v202 offset:576
	ds_read_b32 v188, v202 offset:640
	ds_read_b32 v189, v202 offset:704
	ds_read_b32 v190, v202 offset:768
	ds_read_b32 v191, v202 offset:832
	ds_read_b32 v192, v202 offset:896
	ds_read_b32 v193, v202 offset:960
	s_waitcnt lgkmcnt(12)
	v_add_u32_e32 v172, v172, v200
	global_load_dwordx4 v[16:19], v172, s[14:15]
	v_add_u32_e32 v173, v173, v200
	global_load_dwordx4 v[24:27], v173, s[14:15]
	v_add_u32_e32 v174, v174, v200
	global_load_dwordx4 v[32:35], v174, s[14:15]
	v_add_u32_e32 v175, v175, v200
	global_load_dwordx4 v[40:43], v175, s[14:15]
	s_waitcnt lgkmcnt(8)
	v_add_u32_e32 v176, v176, v200
	global_load_dwordx4 v[48:51], v176, s[14:15]
	v_add_u32_e32 v177, v177, v200
	global_load_dwordx4 v[56:59], v177, s[14:15]
	v_add_u32_e32 v178, v178, v200
	global_load_dwordx4 v[64:67], v178, s[14:15]
	v_add_u32_e32 v179, v179, v200
	global_load_dwordx4 v[72:75], v179, s[14:15]
	s_waitcnt lgkmcnt(4)
	v_add_u32_e32 v180, v180, v200
	global_load_dwordx4 v[90:93], v180, s[14:15]
	v_add_u32_e32 v181, v181, v200
	global_load_dwordx4 v[98:101], v181, s[14:15]
	v_add_u32_e32 v188, v188, v200
	global_load_dwordx4 v[106:109], v188, s[14:15]
	v_add_u32_e32 v189, v189, v200
	global_load_dwordx4 v[114:117], v189, s[14:15]
	s_waitcnt lgkmcnt(0)
	v_add_u32_e32 v190, v190, v200
	global_load_dwordx4 v[122:125], v190, s[14:15]
	v_add_u32_e32 v191, v191, v200
	global_load_dwordx4 v[132:135], v191, s[14:15]
	v_add_u32_e32 v192, v192, v200
	global_load_dwordx4 v[140:143], v192, s[14:15]
	v_add_u32_e32 v193, v193, v200
	global_load_dwordx4 v[148:151], v193, s[14:15]
	ds_read_b32 v172, v202 offset:32
	ds_read_b32 v173, v202 offset:96
	ds_read_b32 v174, v202 offset:160
	ds_read_b32 v175, v202 offset:224
	ds_read_b32 v176, v202 offset:288
	ds_read_b32 v177, v202 offset:352
	ds_read_b32 v178, v202 offset:416
	ds_read_b32 v179, v202 offset:480
	ds_read_b32 v180, v202 offset:544
	ds_read_b32 v181, v202 offset:608
	ds_read_b32 v188, v202 offset:672
	ds_read_b32 v189, v202 offset:736
	ds_read_b32 v190, v202 offset:800
	ds_read_b32 v191, v202 offset:864
	ds_read_b32 v192, v202 offset:928
	ds_read_b32 v193, v202 offset:992
	s_waitcnt lgkmcnt(12)
	v_add_u32_e32 v172, v172, v200
	global_load_dwordx4 v[20:23], v172, s[14:15]
	v_add_u32_e32 v173, v173, v200
	global_load_dwordx4 v[28:31], v173, s[14:15]
	v_add_u32_e32 v174, v174, v200
	global_load_dwordx4 v[36:39], v174, s[14:15]
	v_add_u32_e32 v175, v175, v200
	global_load_dwordx4 v[44:47], v175, s[14:15]
	s_waitcnt lgkmcnt(8)
	v_add_u32_e32 v176, v176, v200
	global_load_dwordx4 v[52:55], v176, s[14:15]
	v_add_u32_e32 v177, v177, v200
	global_load_dwordx4 v[60:63], v177, s[14:15]
	v_add_u32_e32 v178, v178, v200
	global_load_dwordx4 v[68:71], v178, s[14:15]
	v_add_u32_e32 v179, v179, v200
	global_load_dwordx4 v[76:79], v179, s[14:15]
	s_waitcnt lgkmcnt(4)
	v_add_u32_e32 v180, v180, v200
	global_load_dwordx4 v[94:97], v180, s[14:15]
	v_add_u32_e32 v181, v181, v200
	global_load_dwordx4 v[102:105], v181, s[14:15]
	v_add_u32_e32 v188, v188, v200
	global_load_dwordx4 v[110:113], v188, s[14:15]
	v_add_u32_e32 v189, v189, v200
	global_load_dwordx4 v[118:121], v189, s[14:15]
	s_waitcnt lgkmcnt(0)
	v_add_u32_e32 v190, v190, v200
	global_load_dwordx4 v[128:131], v190, s[14:15]
	v_add_u32_e32 v191, v191, v200
	global_load_dwordx4 v[136:139], v191, s[14:15]
	v_add_u32_e32 v192, v192, v200
	global_load_dwordx4 v[144:147], v192, s[14:15]
	v_add_u32_e32 v193, v193, v200
	global_load_dwordx4 v[152:155], v193, s[14:15]
	v_lshl_add_u32 v81, v160, 5, v167
	v_readfirstlane_b32 s2, v85
	s_nop 1
	s_cmp_eq_u32 s2, 0x100
	s_cbranch_scc1 .Lqk_full
;   __device__ __forceinline__ half_t* mm() const { return (half_t*)(ws() + OFF_mm); }
; __device__ __forceinline__ void dsa_item(const KP& p, int b, int tile, char* smem) {
;     ...
; #pragma unroll
;       for (int mm = 0; mm < 8; ++mm) {
;         const int m = mg * 8 + mm;
;         const int pos = m * 16 + col;
;         const int s = (pos < nsel) ? (int)sel[tk * 256 + pos] : 0;
;         const half_t* kp = ub + (size_t)s * NU + C_BK + hq * 8;
;         const h8 a0 = *(const h8*)kp, a1 = *(const h8*)(kp + 32);
;         f32x4 d = {0.f, 0.f, 0.f, 0.f};
;         d = __builtin_amdgcn_mfma_f32_16x16x32_f16(a0, q0, d, 0, 0, 0);
;         d = __builtin_amdgcn_mfma_f32_16x16x32_f16(a1, q1, d, 0, 0, 0);
; #pragma unroll
;         for (int r = 0; r < 4; ++r) {
;           const int pp = m * 16 + hq * 4 + r;
;           const float v = (pp < nsel) ? d[r] * 0.125f : NEGF;
;           mx = fmaxf(mx, v);
;           if (col < 8) pbuf[pp * 8 + col] = v;
;         }
	s_waitcnt vmcnt(15)
	ds_write_b128 v198, v[16:19]
	ds_write_b128 v198, v[20:23] offset:1152
	ds_read_b128 v[16:19], v199
	ds_read_b128 v[20:23], v199 offset:64
	s_waitcnt vmcnt(14)
	ds_write_b128 v198, v[24:27]
	ds_write_b128 v198, v[28:31] offset:1152
	ds_read_b128 v[24:27], v199
	ds_read_b128 v[28:31], v199 offset:64
	s_waitcnt lgkmcnt(4)
	v_mfma_f32_16x16x32_f16 v[10:13], v[16:19], v[6:9], 0
	v_mfma_f32_16x16x32_f16 v[10:13], v[20:23], v[2:5], v[10:13]
	s_nop 4
	s_waitcnt vmcnt(13)
	ds_write_b128 v198, v[32:35]
	ds_write_b128 v198, v[36:39] offset:1152
	ds_read_b128 v[32:35], v199
	ds_read_b128 v[36:39], v199 offset:64
	s_waitcnt lgkmcnt(4)
	v_mfma_f32_16x16x32_f16 v[194:197], v[24:27], v[6:9], 0
	v_mfma_f32_16x16x32_f16 v[194:197], v[28:31], v[2:5], v[194:197]
	v_or_b32_e32 v80, 0, v160
	v_cmp_lt_i32_e32 vcc, v80, v85
	v_cmp_lt_i32_e64 s[46:47], v80, v171
	s_nop 1
	v_cndmask_b32_e32 v10, v242, v10, vcc
	v_cndmask_b32_e64 v11, v242, v11, s[46:47]
	v_cmp_lt_i32_e32 vcc, v80, v156
	v_cmp_lt_i32_e64 s[46:47], v80, v158
	v_max3_f32 v15, v15, v10, v11
	s_nop 0
	v_cndmask_b32_e32 v12, v242, v12, vcc
	v_cndmask_b32_e64 v13, v242, v13, s[46:47]
	v_max3_f32 v15, v15, v12, v13
	s_and_saveexec_b64 s[2:3], s[38:39]
	ds_write_b32 v81, v10
	ds_write_b32 v81, v11 offset:32
	ds_write_b32 v81, v12 offset:64
	ds_write_b32 v81, v13 offset:96
	s_or_b64 exec, exec, s[2:3]
	s_waitcnt vmcnt(12)
	ds_write_b128 v198, v[40:43]
	ds_write_b128 v198, v[44:47] offset:1152
	ds_read_b128 v[40:43], v199
	ds_read_b128 v[44:47], v199 offset:64
	s_waitcnt lgkmcnt(8)
	v_mfma_f32_16x16x32_f16 v[10:13], v[32:35], v[6:9], 0
	v_mfma_f32_16x16x32_f16 v[10:13], v[36:39], v[2:5], v[10:13]
	v_or_b32_e32 v80, 16, v160
	v_cmp_lt_i32_e32 vcc, v80, v85
	v_cmp_lt_i32_e64 s[46:47], v80, v171
	s_nop 1
	v_cndmask_b32_e32 v194, v242, v194, vcc
	v_cndmask_b32_e64 v195, v242, v195, s[46:47]
	v_cmp_lt_i32_e32 vcc, v80, v156
	v_cmp_lt_i32_e64 s[46:47], v80, v158
	v_max3_f32 v15, v15, v194, v195
	s_nop 0
	v_cndmask_b32_e32 v196, v242, v196, vcc
	v_cndmask_b32_e64 v197, v242, v197, s[46:47]
	v_max3_f32 v15, v15, v196, v197
	s_and_saveexec_b64 s[2:3], s[38:39]
	ds_write_b32 v81, v194 offset:512
	ds_write_b32 v81, v195 offset:544
	ds_write_b32 v81, v196 offset:576
	ds_write_b32 v81, v197 offset:608
	s_or_b64 exec, exec, s[2:3]
	s_waitcnt vmcnt(11)
	ds_write_b128 v198, v[48:51]
	ds_write_b128 v198, v[52:55] offset:1152
	ds_read_b128 v[48:51], v199
	ds_read_b128 v[52:55], v199 offset:64
	s_waitcnt lgkmcnt(8)
	v_mfma_f32_16x16x32_f16 v[194:197], v[40:43], v[6:9], 0
	v_mfma_f32_16x16x32_f16 v[194:197], v[44:47], v[2:5], v[194:197]
	v_or_b32_e32 v80, 32, v160
	v_cmp_lt_i32_e32 vcc, v80, v85
	v_cmp_lt_i32_e64 s[46:47], v80, v171
	s_nop 1
	v_cndmask_b32_e32 v10, v242, v10, vcc
	v_cndmask_b32_e64 v11, v242, v11, s[46:47]
	v_cmp_lt_i32_e32 vcc, v80, v156
	v_cmp_lt_i32_e64 s[46:47], v80, v158
	v_max3_f32 v15, v15, v10, v11
	s_nop 0
	v_cndmask_b32_e32 v12, v242, v12, vcc
	v_cndmask_b32_e64 v13, v242, v13, s[46:47]
	v_max3_f32 v15, v15, v12, v13
	s_and_saveexec_b64 s[2:3], s[38:39]
	ds_write_b32 v81, v10 offset:1024
	ds_write_b32 v81, v11 offset:1056
	ds_write_b32 v81, v12 offset:1088
	ds_write_b32 v81, v13 offset:1120
	s_or_b64 exec, exec, s[2:3]
	s_waitcnt vmcnt(10)
	ds_write_b128 v198, v[56:59]
	ds_write_b128 v198, v[60:63] offset:1152
	ds_read_b128 v[56:59], v199
	ds_read_b128 v[60:63], v199 offset:64
	s_waitcnt lgkmcnt(8)
	v_mfma_f32_16x16x32_f16 v[10:13], v[48:51], v[6:9], 0
	v_mfma_f32_16x16x32_f16 v[10:13], v[52:55], v[2:5], v[10:13]
	v_or_b32_e32 v80, 48, v160
	v_cmp_lt_i32_e32 vcc, v80, v85
	v_cmp_lt_i32_e64 s[46:47], v80, v171
	s_nop 1
	v_cndmask_b32_e32 v194, v242, v194, vcc
	v_cndmask_b32_e64 v195, v242, v195, s[46:47]
	v_cmp_lt_i32_e32 vcc, v80, v156
	v_cmp_lt_i32_e64 s[46:47], v80, v158
	v_max3_f32 v15, v15, v194, v195
	s_nop 0
	v_cndmask_b32_e32 v196, v242, v196, vcc
	v_cndmask_b32_e64 v197, v242, v197, s[46:47]
	v_max3_f32 v15, v15, v196, v197
	s_and_saveexec_b64 s[2:3], s[38:39]
	ds_write_b32 v81, v194 offset:1536
	ds_write_b32 v81, v195 offset:1568
	ds_write_b32 v81, v196 offset:1600
	ds_write_b32 v81, v197 offset:1632
	s_or_b64 exec, exec, s[2:3]
	s_waitcnt vmcnt(9)
	ds_write_b128 v198, v[64:67]
	ds_write_b128 v198, v[68:71] offset:1152
	ds_read_b128 v[64:67], v199
	ds_read_b128 v[68:71], v199 offset:64
	s_waitcnt lgkmcnt(8)
	v_mfma_f32_16x16x32_f16 v[194:197], v[56:59], v[6:9], 0
	v_mfma_f32_16x16x32_f16 v[194:197], v[60:63], v[2:5], v[194:197]
	v_or_b32_e32 v80, 64, v160
	v_cmp_lt_i32_e32 vcc, v80, v85
	v_cmp_lt_i32_e64 s[46:47], v80, v171
	s_nop 1
	v_cndmask_b32_e32 v10, v242, v10, vcc
	v_cndmask_b32_e64 v11, v242, v11, s[46:47]
	v_cmp_lt_i32_e32 vcc, v80, v156
	v_cmp_lt_i32_e64 s[46:47], v80, v158
	v_max3_f32 v15, v15, v10, v11
	s_nop 0
	v_cndmask_b32_e32 v12, v242, v12, vcc
	v_cndmask_b32_e64 v13, v242, v13, s[46:47]
	v_max3_f32 v15, v15, v12, v13
	s_and_saveexec_b64 s[2:3], s[38:39]
	ds_write_b32 v81, v10 offset:2048
	ds_write_b32 v81, v11 offset:2080
	ds_write_b32 v81, v12 offset:2112
	ds_write_b32 v81, v13 offset:2144
	s_or_b64 exec, exec, s[2:3]
	s_waitcnt vmcnt(8)
	ds_write_b128 v198, v[72:75]
	ds_write_b128 v198, v[76:79] offset:1152
	ds_read_b128 v[72:75], v199
	ds_read_b128 v[76:79], v199 offset:64
	s_waitcnt lgkmcnt(8)
;   __device__ __forceinline__ half_t* mm() const { return (half_t*)(ws() + OFF_mm); }
; __device__ __forceinline__ void dsa_item(const KP& p, int b, int tile, char* smem) {
;     ...
; #pragma unroll
;       for (int mm = 0; mm < 8; ++mm) {
;         const int m = mg * 8 + mm;
;         const int pos = m * 16 + col;
;         const int s = (pos < nsel) ? (int)sel[tk * 256 + pos] : 0;
;         const half_t* kp = ub + (size_t)s * NU + C_BK + hq * 8;
;         const h8 a0 = *(const h8*)kp, a1 = *(const h8*)(kp + 32);
;         f32x4 d = {0.f, 0.f, 0.f, 0.f};
;         d = __builtin_amdgcn_mfma_f32_16x16x32_f16(a0, q0, d, 0, 0, 0);
;         d = __builtin_amdgcn_mfma_f32_16x16x32_f16(a1, q1, d, 0, 0, 0);
; #pragma unroll
;         for (int r = 0; r < 4; ++r) {
;           const int pp = m * 16 + hq * 4 + r;
;           const float v = (pp < nsel) ? d[r] * 0.125f : NEGF;
;           mx = fmaxf(mx, v);
;           if (col < 8) pbuf[pp * 8 + col] = v;
;         }
	v_mfma_f32_16x16x32_f16 v[10:13], v[64:67], v[6:9], 0
	v_mfma_f32_16x16x32_f16 v[10:13], v[68:71], v[2:5], v[10:13]
	v_or_b32_e32 v80, 0x50, v160
	v_cmp_lt_i32_e32 vcc, v80, v85
	v_cmp_lt_i32_e64 s[46:47], v80, v171
	s_nop 1
	v_cndmask_b32_e32 v194, v242, v194, vcc
	v_cndmask_b32_e64 v195, v242, v195, s[46:47]
	v_cmp_lt_i32_e32 vcc, v80, v156
	v_cmp_lt_i32_e64 s[46:47], v80, v158
	v_max3_f32 v15, v15, v194, v195
	s_nop 0
	v_cndmask_b32_e32 v196, v242, v196, vcc
	v_cndmask_b32_e64 v197, v242, v197, s[46:47]
	v_max3_f32 v15, v15, v196, v197
	s_and_saveexec_b64 s[2:3], s[38:39]
	ds_write_b32 v81, v194 offset:2560
	ds_write_b32 v81, v195 offset:2592
	ds_write_b32 v81, v196 offset:2624
	ds_write_b32 v81, v197 offset:2656
	s_or_b64 exec, exec, s[2:3]
	s_waitcnt vmcnt(7)
	ds_write_b128 v198, v[90:93]
	ds_write_b128 v198, v[94:97] offset:1152
	ds_read_b128 v[90:93], v199
	ds_read_b128 v[94:97], v199 offset:64
	s_waitcnt lgkmcnt(8)
	v_mfma_f32_16x16x32_f16 v[194:197], v[72:75], v[6:9], 0
	v_mfma_f32_16x16x32_f16 v[194:197], v[76:79], v[2:5], v[194:197]
	v_or_b32_e32 v80, 0x60, v160
	v_cmp_lt_i32_e32 vcc, v80, v85
	v_cmp_lt_i32_e64 s[46:47], v80, v171
	s_nop 1
	v_cndmask_b32_e32 v10, v242, v10, vcc
	v_cndmask_b32_e64 v11, v242, v11, s[46:47]
	v_cmp_lt_i32_e32 vcc, v80, v156
	v_cmp_lt_i32_e64 s[46:47], v80, v158
	v_max3_f32 v15, v15, v10, v11
	s_nop 0
	v_cndmask_b32_e32 v12, v242, v12, vcc
	v_cndmask_b32_e64 v13, v242, v13, s[46:47]
	v_max3_f32 v15, v15, v12, v13
	s_and_saveexec_b64 s[2:3], s[38:39]
	ds_write_b32 v81, v10 offset:3072
	ds_write_b32 v81, v11 offset:3104
	ds_write_b32 v81, v12 offset:3136
	ds_write_b32 v81, v13 offset:3168
	s_or_b64 exec, exec, s[2:3]
	s_waitcnt vmcnt(6)
	ds_write_b128 v198, v[98:101]
	ds_write_b128 v198, v[102:105] offset:1152
	ds_read_b128 v[98:101], v199
	ds_read_b128 v[102:105], v199 offset:64
	s_waitcnt lgkmcnt(8)
	v_mfma_f32_16x16x32_f16 v[10:13], v[90:93], v[6:9], 0
	v_mfma_f32_16x16x32_f16 v[10:13], v[94:97], v[2:5], v[10:13]
	v_or_b32_e32 v80, 0x70, v160
	v_cmp_lt_i32_e32 vcc, v80, v85
	v_cmp_lt_i32_e64 s[46:47], v80, v171
	s_nop 1
	v_cndmask_b32_e32 v194, v242, v194, vcc
	v_cndmask_b32_e64 v195, v242, v195, s[46:47]
	v_cmp_lt_i32_e32 vcc, v80, v156
	v_cmp_lt_i32_e64 s[46:47], v80, v158
	v_max3_f32 v15, v15, v194, v195
	s_nop 0
	v_cndmask_b32_e32 v196, v242, v196, vcc
	v_cndmask_b32_e64 v197, v242, v197, s[46:47]
	v_max3_f32 v15, v15, v196, v197
	s_and_saveexec_b64 s[2:3], s[38:39]
	ds_write_b32 v81, v194 offset:3584
	ds_write_b32 v81, v195 offset:3616
	ds_write_b32 v81, v196 offset:3648
	ds_write_b32 v81, v197 offset:3680
	s_or_b64 exec, exec, s[2:3]
	s_waitcnt vmcnt(5)
	ds_write_b128 v198, v[106:109]
	ds_write_b128 v198, v[110:113] offset:1152
	ds_read_b128 v[106:109], v199
	ds_read_b128 v[110:113], v199 offset:64
	s_waitcnt lgkmcnt(8)
	v_mfma_f32_16x16x32_f16 v[194:197], v[98:101], v[6:9], 0
	v_mfma_f32_16x16x32_f16 v[194:197], v[102:105], v[2:5], v[194:197]
	v_or_b32_e32 v80, 0x80, v160
	v_cmp_lt_i32_e32 vcc, v80, v85
	v_cmp_lt_i32_e64 s[46:47], v80, v171
	s_nop 1
	v_cndmask_b32_e32 v10, v242, v10, vcc
	v_cndmask_b32_e64 v11, v242, v11, s[46:47]
	v_cmp_lt_i32_e32 vcc, v80, v156
	v_cmp_lt_i32_e64 s[46:47], v80, v158
	v_max3_f32 v15, v15, v10, v11
	s_nop 0
	v_cndmask_b32_e32 v12, v242, v12, vcc
	v_cndmask_b32_e64 v13, v242, v13, s[46:47]
	v_max3_f32 v15, v15, v12, v13
	s_and_saveexec_b64 s[2:3], s[38:39]
	ds_write_b32 v81, v10 offset:4096
	ds_write_b32 v81, v11 offset:4128
	ds_write_b32 v81, v12 offset:4160
	ds_write_b32 v81, v13 offset:4192
	s_or_b64 exec, exec, s[2:3]
	s_waitcnt vmcnt(4)
	ds_write_b128 v198, v[114:117]
	ds_write_b128 v198, v[118:121] offset:1152
	ds_read_b128 v[114:117], v199
	ds_read_b128 v[118:121], v199 offset:64
	s_waitcnt lgkmcnt(8)
	v_mfma_f32_16x16x32_f16 v[10:13], v[106:109], v[6:9], 0
	v_mfma_f32_16x16x32_f16 v[10:13], v[110:113], v[2:5], v[10:13]
	v_or_b32_e32 v80, 0x90, v160
	v_cmp_lt_i32_e32 vcc, v80, v85
	v_cmp_lt_i32_e64 s[46:47], v80, v171
	s_nop 1
	v_cndmask_b32_e32 v194, v242, v194, vcc
	v_cndmask_b32_e64 v195, v242, v195, s[46:47]
	v_cmp_lt_i32_e32 vcc, v80, v156
	v_cmp_lt_i32_e64 s[46:47], v80, v158
	v_max3_f32 v15, v15, v194, v195
	s_nop 0
	v_cndmask_b32_e32 v196, v242, v196, vcc
	v_cndmask_b32_e64 v197, v242, v197, s[46:47]
	v_max3_f32 v15, v15, v196, v197
	s_and_saveexec_b64 s[2:3], s[38:39]
	ds_write_b32 v81, v194 offset:4608
	ds_write_b32 v81, v195 offset:4640
	ds_write_b32 v81, v196 offset:4672
	ds_write_b32 v81, v197 offset:4704
	s_or_b64 exec, exec, s[2:3]
	s_waitcnt vmcnt(3)
	ds_write_b128 v198, v[122:125]
	ds_write_b128 v198, v[128:131] offset:1152
	ds_read_b128 v[122:125], v199
	ds_read_b128 v[128:131], v199 offset:64
	s_waitcnt lgkmcnt(8)
;   __device__ __forceinline__ half_t* mm() const { return (half_t*)(ws() + OFF_mm); }
; __device__ __forceinline__ void dsa_item(const KP& p, int b, int tile, char* smem) {
;     ...
; #pragma unroll
;       for (int mm = 0; mm < 8; ++mm) {
;         const int m = mg * 8 + mm;
;         const int pos = m * 16 + col;
;         const int s = (pos < nsel) ? (int)sel[tk * 256 + pos] : 0;
;         const half_t* kp = ub + (size_t)s * NU + C_BK + hq * 8;
;         const h8 a0 = *(const h8*)kp, a1 = *(const h8*)(kp + 32);
;         f32x4 d = {0.f, 0.f, 0.f, 0.f};
;         d = __builtin_amdgcn_mfma_f32_16x16x32_f16(a0, q0, d, 0, 0, 0);
;         d = __builtin_amdgcn_mfma_f32_16x16x32_f16(a1, q1, d, 0, 0, 0);
; #pragma unroll
;         for (int r = 0; r < 4; ++r) {
;           const int pp = m * 16 + hq * 4 + r;
;           const float v = (pp < nsel) ? d[r] * 0.125f : NEGF;
;           mx = fmaxf(mx, v);
;           if (col < 8) pbuf[pp * 8 + col] = v;
;         }
	v_mfma_f32_16x16x32_f16 v[194:197], v[114:117], v[6:9], 0
	v_mfma_f32_16x16x32_f16 v[194:197], v[118:121], v[2:5], v[194:197]
	v_or_b32_e32 v80, 0xa0, v160
	v_cmp_lt_i32_e32 vcc, v80, v85
	v_cmp_lt_i32_e64 s[46:47], v80, v171
	s_nop 1
	v_cndmask_b32_e32 v10, v242, v10, vcc
	v_cndmask_b32_e64 v11, v242, v11, s[46:47]
	v_cmp_lt_i32_e32 vcc, v80, v156
	v_cmp_lt_i32_e64 s[46:47], v80, v158
	v_max3_f32 v15, v15, v10, v11
	s_nop 0
	v_cndmask_b32_e32 v12, v242, v12, vcc
	v_cndmask_b32_e64 v13, v242, v13, s[46:47]
	v_max3_f32 v15, v15, v12, v13
	s_and_saveexec_b64 s[2:3], s[38:39]
	ds_write_b32 v81, v10 offset:5120
	ds_write_b32 v81, v11 offset:5152
	ds_write_b32 v81, v12 offset:5184
	ds_write_b32 v81, v13 offset:5216
	s_or_b64 exec, exec, s[2:3]
	s_waitcnt vmcnt(2)
	ds_write_b128 v198, v[132:135]
	ds_write_b128 v198, v[136:139] offset:1152
	ds_read_b128 v[132:135], v199
	ds_read_b128 v[136:139], v199 offset:64
	s_waitcnt lgkmcnt(8)
	v_mfma_f32_16x16x32_f16 v[10:13], v[122:125], v[6:9], 0
	v_mfma_f32_16x16x32_f16 v[10:13], v[128:131], v[2:5], v[10:13]
	v_or_b32_e32 v80, 0xb0, v160
	v_cmp_lt_i32_e32 vcc, v80, v85
	v_cmp_lt_i32_e64 s[46:47], v80, v171
	s_nop 1
	v_cndmask_b32_e32 v194, v242, v194, vcc
	v_cndmask_b32_e64 v195, v242, v195, s[46:47]
	v_cmp_lt_i32_e32 vcc, v80, v156
	v_cmp_lt_i32_e64 s[46:47], v80, v158
	v_max3_f32 v15, v15, v194, v195
	s_nop 0
	v_cndmask_b32_e32 v196, v242, v196, vcc
	v_cndmask_b32_e64 v197, v242, v197, s[46:47]
	v_max3_f32 v15, v15, v196, v197
	s_and_saveexec_b64 s[2:3], s[38:39]
	ds_write_b32 v81, v194 offset:5632
	ds_write_b32 v81, v195 offset:5664
	ds_write_b32 v81, v196 offset:5696
	ds_write_b32 v81, v197 offset:5728
	s_or_b64 exec, exec, s[2:3]
	s_waitcnt vmcnt(1)
	ds_write_b128 v198, v[140:143]
	ds_write_b128 v198, v[144:147] offset:1152
	ds_read_b128 v[140:143], v199
	ds_read_b128 v[144:147], v199 offset:64
	s_waitcnt lgkmcnt(8)
	v_mfma_f32_16x16x32_f16 v[194:197], v[132:135], v[6:9], 0
	v_mfma_f32_16x16x32_f16 v[194:197], v[136:139], v[2:5], v[194:197]
	v_or_b32_e32 v80, 0xc0, v160
	v_cmp_lt_i32_e32 vcc, v80, v85
	v_cmp_lt_i32_e64 s[46:47], v80, v171
	s_nop 1
	v_cndmask_b32_e32 v10, v242, v10, vcc
	v_cndmask_b32_e64 v11, v242, v11, s[46:47]
	v_cmp_lt_i32_e32 vcc, v80, v156
	v_cmp_lt_i32_e64 s[46:47], v80, v158
	v_max3_f32 v15, v15, v10, v11
	s_nop 0
	v_cndmask_b32_e32 v12, v242, v12, vcc
	v_cndmask_b32_e64 v13, v242, v13, s[46:47]
	v_max3_f32 v15, v15, v12, v13
	s_and_saveexec_b64 s[2:3], s[38:39]
	ds_write_b32 v81, v10 offset:6144
	ds_write_b32 v81, v11 offset:6176
	ds_write_b32 v81, v12 offset:6208
	ds_write_b32 v81, v13 offset:6240
	s_or_b64 exec, exec, s[2:3]
	s_waitcnt vmcnt(0)
	ds_write_b128 v198, v[148:151]
	ds_write_b128 v198, v[152:155] offset:1152
	ds_read_b128 v[148:151], v199
	ds_read_b128 v[152:155], v199 offset:64
	s_waitcnt lgkmcnt(8)
	v_mfma_f32_16x16x32_f16 v[10:13], v[140:143], v[6:9], 0
	v_mfma_f32_16x16x32_f16 v[10:13], v[144:147], v[2:5], v[10:13]
	v_or_b32_e32 v80, 0xd0, v160
	v_cmp_lt_i32_e32 vcc, v80, v85
	v_cmp_lt_i32_e64 s[46:47], v80, v171
	s_nop 1
	v_cndmask_b32_e32 v194, v242, v194, vcc
	v_cndmask_b32_e64 v195, v242, v195, s[46:47]
	v_cmp_lt_i32_e32 vcc, v80, v156
	v_cmp_lt_i32_e64 s[46:47], v80, v158
	v_max3_f32 v15, v15, v194, v195
	s_nop 0
	v_cndmask_b32_e32 v196, v242, v196, vcc
	v_cndmask_b32_e64 v197, v242, v197, s[46:47]
	v_max3_f32 v15, v15, v196, v197
	s_and_saveexec_b64 s[2:3], s[38:39]
	ds_write_b32 v81, v194 offset:6656
	ds_write_b32 v81, v195 offset:6688
	ds_write_b32 v81, v196 offset:6720
	ds_write_b32 v81, v197 offset:6752
	s_or_b64 exec, exec, s[2:3]
	s_waitcnt lgkmcnt(4)
	v_mfma_f32_16x16x32_f16 v[194:197], v[148:151], v[6:9], 0
	v_mfma_f32_16x16x32_f16 v[194:197], v[152:155], v[2:5], v[194:197]
	v_or_b32_e32 v80, 0xe0, v160
	v_cmp_lt_i32_e32 vcc, v80, v85
	v_cmp_lt_i32_e64 s[46:47], v80, v171
	s_nop 1
	v_cndmask_b32_e32 v10, v242, v10, vcc
	v_cndmask_b32_e64 v11, v242, v11, s[46:47]
	v_cmp_lt_i32_e32 vcc, v80, v156
	v_cmp_lt_i32_e64 s[46:47], v80, v158
	v_max3_f32 v15, v15, v10, v11
	s_nop 0
	v_cndmask_b32_e32 v12, v242, v12, vcc
	v_cndmask_b32_e64 v13, v242, v13, s[46:47]
	v_max3_f32 v15, v15, v12, v13
	s_and_saveexec_b64 s[2:3], s[38:39]
	ds_write_b32 v81, v10 offset:7168
	ds_write_b32 v81, v11 offset:7200
	ds_write_b32 v81, v12 offset:7232
	ds_write_b32 v81, v13 offset:7264
	s_or_b64 exec, exec, s[2:3]
	s_nop 7
	v_or_b32_e32 v80, 0xf0, v160
	v_cmp_lt_i32_e32 vcc, v80, v85
	v_cmp_lt_i32_e64 s[46:47], v80, v171
	s_nop 1
	v_cndmask_b32_e32 v194, v242, v194, vcc
	v_cndmask_b32_e64 v195, v242, v195, s[46:47]
	v_cmp_lt_i32_e32 vcc, v80, v156
	v_cmp_lt_i32_e64 s[46:47], v80, v158
	v_max3_f32 v15, v15, v194, v195
	s_nop 0
	v_cndmask_b32_e32 v196, v242, v196, vcc
	v_cndmask_b32_e64 v197, v242, v197, s[46:47]
	v_max3_f32 v15, v15, v196, v197
	s_and_saveexec_b64 s[2:3], s[38:39]
	ds_write_b32 v81, v194 offset:7680
	ds_write_b32 v81, v195 offset:7712
	ds_write_b32 v81, v196 offset:7744
	ds_write_b32 v81, v197 offset:7776
	s_or_b64 exec, exec, s[2:3]
	s_branch .LBB0_1509
